# attention loop: prefetch lane offsets hoisted out of the tile loop; neighbourhood bias applied in place (no 16-register copy back per local tile)
# speedup vs baseline: 1.0037x; 1.0037x over previous
.LBB0_390:
	s_or_b64 exec, exec, s[8:9]
	v_add_u32_e32 v10, v5, v142
	v_ashrrev_i32_e32 v11, 31, v10
	v_and_b32_e32 v1, 7, v1
	v_lshlrev_b64 v[122:123], 10, v[10:11]
	v_lshl_add_u64 v[10:11], s[16:17], 0, v[122:123]
	v_lshlrev_b32_e32 v112, 7, v1
	v_lshl_add_u64 v[10:11], v[10:11], 0, v[112:113]
	v_mov_b32_e32 v119, v113
	v_lshl_add_u64 v[10:11], v[10:11], 0, v[118:119]
	v_ashrrev_i32_e32 v7, 31, v6
	global_load_dwordx4 v[64:67], v[10:11], off
	global_load_dwordx4 v[68:71], v[10:11], off offset:32
	global_load_dwordx4 v[72:75], v[10:11], off offset:64
	global_load_dwordx4 v[76:79], v[10:11], off offset:96
	v_lshlrev_b64 v[10:11], 19, v[6:7]
	v_lshl_or_b32 v6, v6, 3, v1
	v_lshl_add_u64 v[10:11], s[20:21], 0, v[10:11]
	v_ashrrev_i32_e32 v7, 31, v6
	v_ashrrev_i32_e32 v5, 31, v4
	v_lshl_add_u64 v[124:125], v[10:11], 0, v[112:113]
	v_lshlrev_b64 v[10:11], 16, v[6:7]
	v_lshlrev_b64 v[4:5], 10, v[4:5]
	v_lshl_add_u64 v[126:127], s[26:27], 0, v[10:11]
	v_lshl_add_u64 v[10:11], s[18:19], 0, v[4:5]
	v_mov_b32_e32 v3, v131
	v_lshl_add_u64 v[10:11], v[10:11], 0, v[112:113]
	v_lshlrev_b64 v[12:13], 15, v[6:7]
	v_lshl_add_u64 v[128:129], s[30:31], 0, v[12:13]
	v_lshlrev_b32_e32 v16, 4, v3
	v_cndmask_b32_e32 v11, v125, v11, vcc
	v_cndmask_b32_e32 v10, v124, v10, vcc
	v_and_b32_e32 v14, 0x70, v16
	v_mov_b32_e32 v15, v113
	v_cndmask_b32_e32 v13, v127, v129, vcc
	v_cndmask_b32_e32 v12, v126, v128, vcc
	v_lshl_add_u64 v[10:11], v[10:11], 0, v[14:15]
	v_and_b32_e32 v14, 48, v16
	v_lshl_add_u64 v[12:13], v[12:13], 0, v[14:15]
	v_ashrrev_i32_e32 v14, 3, v3
	v_ashrrev_i32_e32 v15, 31, v14
	v_lshlrev_b64 v[14:15], 10, v[14:15]
	v_lshl_add_u64 v[14:15], v[10:11], 0, v[14:15]
	global_load_dwordx4 v[80:83], v[14:15], off
	v_ashrrev_i32_e32 v14, 2, v3
	v_ashrrev_i32_e32 v15, 31, v14
	v_lshlrev_b64 v[14:15], v2, v[14:15]
	v_lshl_add_u64 v[14:15], v[14:15], 1, v[12:13]
	v_add_u32_e32 v16, 64, v3
	global_load_dwordx4 v[84:87], v[14:15], off
	v_ashrrev_i32_e32 v14, 3, v16
	v_ashrrev_i32_e32 v15, 31, v14
	v_lshlrev_b64 v[14:15], 10, v[14:15]
	v_lshl_add_u64 v[14:15], v[10:11], 0, v[14:15]
	global_load_dwordx4 v[88:91], v[14:15], off
	v_ashrrev_i32_e32 v14, 2, v16
	v_ashrrev_i32_e32 v15, 31, v14
	v_lshlrev_b64 v[14:15], v2, v[14:15]
	v_lshl_add_u64 v[14:15], v[14:15], 1, v[12:13]
	v_add_u32_e32 v16, 0x80, v3
	global_load_dwordx4 v[92:95], v[14:15], off
	v_ashrrev_i32_e32 v14, 3, v16
	v_ashrrev_i32_e32 v15, 31, v14
	v_lshlrev_b64 v[14:15], 10, v[14:15]
	v_lshl_add_u64 v[14:15], v[10:11], 0, v[14:15]
	global_load_dwordx4 v[96:99], v[14:15], off
	v_ashrrev_i32_e32 v14, 2, v16
	v_ashrrev_i32_e32 v15, 31, v14
	v_lshlrev_b64 v[14:15], v2, v[14:15]
	v_lshl_add_u64 v[14:15], v[14:15], 1, v[12:13]
	v_add_u32_e32 v3, 0xc0, v3
	global_load_dwordx4 v[100:103], v[14:15], off
	v_ashrrev_i32_e32 v14, 3, v3
	v_ashrrev_i32_e32 v15, 31, v14
	v_lshlrev_b64 v[14:15], 10, v[14:15]
	v_lshl_add_u64 v[10:11], v[10:11], 0, v[14:15]
	global_load_dwordx4 v[104:107], v[10:11], off
	v_ashrrev_i32_e32 v10, 2, v3
	v_ashrrev_i32_e32 v11, 31, v10
	v_lshlrev_b64 v[2:3], v2, v[10:11]
	v_lshl_add_u64 v[2:3], v[2:3], 1, v[12:13]
	global_load_dwordx4 v[108:111], v[2:3], off
	v_lshlrev_b32_e32 v130, 6, v1
	v_mul_u32_u24_e32 v1, 0x1d1, v1
	v_lshlrev_b32_e32 v2, 2, v1
	v_sub_u32_e64 v1, v8, 4 clamp
	v_min_u32_e32 v119, 56, v1
	v_ashrrev_i32_e32 v1, 31, v0
	v_lshlrev_b64 v[0:1], 10, v[0:1]
	v_lshl_add_u64 v[0:1], s[18:19], 0, v[0:1]
	v_lshl_add_u64 v[134:135], v[0:1], 0, v[112:113]
	v_lshlrev_b64 v[0:1], 19, v[6:7]
	v_or_b32_e32 v151, v9, v142
	v_lshl_add_u64 v[136:137], s[28:29], 0, v[0:1]
	v_sub_u32_e64 v0, v151, 8 clamp
	v_mov_b32_e32 v3, v113
	v_min_u32_e32 v153, 48, v0
	v_or_b32_e32 v4, v4, v112
	v_mov_b32_e32 v155, 0
	v_lshl_add_u64 v[132:133], s[14:15], 0, v[2:3]
	v_sub_u32_e32 v152, v119, v8
	v_add_u32_e32 v154, 16, v153
	v_lshl_add_u64 v[138:139], s[34:35], 0, v[4:5]
	v_mov_b32_e32 v156, 0xff800000
	s_mov_b32 s65, 0
	s_mov_b32 s63, 32
	s_mov_b64 s[40:41], 0
	s_xor_b64 s[42:43], vcc, -1
	v_mov_b32_e32 v0, 0
	v_mov_b32_e32 v1, v155
	v_mov_b32_e32 v2, v155
	v_mov_b32_e32 v3, v155
	v_mov_b32_e32 v4, v155
	v_mov_b32_e32 v5, v155
	v_mov_b32_e32 v6, v155
	v_mov_b32_e32 v7, v155
	v_mov_b32_e32 v8, v155
	v_mov_b32_e32 v9, v155
	v_mov_b32_e32 v10, v155
	v_mov_b32_e32 v11, v155
	v_mov_b32_e32 v12, v155
	v_mov_b32_e32 v13, v155
	v_mov_b32_e32 v14, v155
	v_mov_b32_e32 v15, v155
	v_mov_b32_e32 v16, 0
	v_mov_b32_e32 v17, v155
	v_mov_b32_e32 v18, v155
	v_mov_b32_e32 v19, v155
	v_mov_b32_e32 v20, v155
	v_mov_b32_e32 v21, v155
	v_mov_b32_e32 v22, v155
	v_mov_b32_e32 v23, v155
	v_mov_b32_e32 v24, v155
	v_mov_b32_e32 v25, v155
	v_mov_b32_e32 v26, v155
	v_mov_b32_e32 v27, v155
	v_mov_b32_e32 v28, v155
	v_mov_b32_e32 v29, v155
	v_mov_b32_e32 v30, v155
	v_mov_b32_e32 v31, v155
	v_lshlrev_b32_e32 v222, 4, v131
	v_and_b32_e32 v220, 0x70, v222
	v_and_b32_e32 v221, 48, v222
	v_lshrrev_b32_e32 v222, 3, v131
	v_mad_u32_u24 v220, v222, s48, v220
	v_add_u32_e32 v220, v143, v220
	v_lshrrev_b32_e32 v222, 2, v131
	v_mad_u32_u24 v221, v222, s61, v221
	v_add_u32_e32 v221, v143, v221
	v_and_b32_e32 v226, 7, v131
	v_lshrrev_b32_e32 v227, 3, v131
	v_lshlrev_b32_e32 v226, 4, v226
	v_lshl_add_u32 v226, v227, 10, v226
	v_and_b32_e32 v227, 3, v131
	v_lshlrev_b32_e32 v227, 4, v227
	v_lshrrev_b32_e32 v228, 2, v131
	s_branch .LBB0_393

.LBB0_400:
	s_or_b64 exec, exec, s[44:45]
	v_lshl_add_u64 v[36:37], v[112:113], 1, v[36:37]
	v_readfirstlane_b32 s68, v34
	v_readfirstlane_b32 s69, v35
	v_readfirstlane_b32 s72, v32
	v_readfirstlane_b32 s70, v36
	v_readfirstlane_b32 s71, v37
	s_lshl_b32 s72, s72, 1
	s_lshl_b32 s73, s72, 4
	v_mad_u32_u24 v216, v228, s72, v227
	s_add_u32 s80, s68, 0x2000
	s_addc_u32 s81, s69, 0
	s_add_u32 s82, s68, 0x4000
	s_addc_u32 s83, s69, 0
	s_add_u32 s84, s68, 0x6000
	s_addc_u32 s85, s69, 0
	s_add_u32 s74, s70, s73
	s_addc_u32 s75, s71, 0
	s_add_u32 s76, s74, s73
	s_addc_u32 s77, s75, 0
	s_add_u32 s78, s76, s73
	s_addc_u32 s79, s77, 0
	global_load_dwordx4 v[80:83], v226, s[68:69]
	global_load_dwordx4 v[84:87], v216, s[70:71]
	global_load_dwordx4 v[88:91], v226, s[80:81]
	global_load_dwordx4 v[92:95], v216, s[74:75]
	global_load_dwordx4 v[96:99], v226, s[82:83]
	global_load_dwordx4 v[100:103], v216, s[76:77]
	global_load_dwordx4 v[104:107], v226, s[84:85]
	global_load_dwordx4 v[108:111], v216, s[78:79]
.LBB0_401:
	s_or_b64 exec, exec, s[8:9]
	s_cmp_gt_u32 s65, 15
	s_cselect_b64 s[8:9], -1, 0
	s_and_b64 s[8:9], s[42:43], s[8:9]
	s_waitcnt lgkmcnt(3)
	v_mfma_f32_32x32x16_bf16 v[32:47], v[158:161], v[64:67], 0
	s_waitcnt lgkmcnt(2)
	v_mfma_f32_32x32x16_bf16 v[32:47], v[162:165], v[68:71], v[32:47]
	s_waitcnt lgkmcnt(1)
	v_mfma_f32_32x32x16_bf16 v[32:47], v[166:169], v[72:75], v[32:47]
	s_waitcnt lgkmcnt(0)
	v_mfma_f32_32x32x16_bf16 v[32:47], v[170:173], v[76:79], v[32:47]
	s_and_saveexec_b64 s[44:45], s[8:9]
	s_cbranch_execz .LBB0_392
	s_add_i32 s9, s65, -16
	s_ashr_i32 s9, s9, 1
	s_sub_i32 s8, s63, 32
	v_add_u32_e32 v48, s9, v152
	v_and_or_b32 v112, s8, 32, v145
	v_mad_u64_u32 v[140:141], s[8:9], v48, 31, v[120:121]
	v_subrev_u32_e32 v207, s14, v132
	v_add_u32_e32 v140, 15, v140
	v_mov_b32_e32 v210, 0xf149f2ca
	v_lshl_add_u32 v207, v140, 2, v207
	v_sub_u32_e32 v188, v112, v151
	v_sub_u32_e32 v189, v112, v153
	v_add_u32_e32 v209, 0, v188
	v_med3_i32 v209, v209, -15, 15
	v_lshl_add_u32 v209, v209, 2, v207
	global_load_dword v190, v209, s[14:15]
	v_add_u32_e32 v209, 1, v188
	v_med3_i32 v209, v209, -15, 15
	v_lshl_add_u32 v209, v209, 2, v207
	global_load_dword v191, v209, s[14:15]
	v_add_u32_e32 v209, 2, v188
	v_med3_i32 v209, v209, -15, 15
	v_lshl_add_u32 v209, v209, 2, v207
	global_load_dword v192, v209, s[14:15]
	v_add_u32_e32 v209, 3, v188
	v_med3_i32 v209, v209, -15, 15
	v_lshl_add_u32 v209, v209, 2, v207
	global_load_dword v193, v209, s[14:15]
	v_add_u32_e32 v209, 8, v188
	v_med3_i32 v209, v209, -15, 15
	v_lshl_add_u32 v209, v209, 2, v207
	global_load_dword v194, v209, s[14:15]
	v_add_u32_e32 v209, 9, v188
	v_med3_i32 v209, v209, -15, 15
	v_lshl_add_u32 v209, v209, 2, v207
	global_load_dword v195, v209, s[14:15]
	v_add_u32_e32 v209, 10, v188
	v_med3_i32 v209, v209, -15, 15
	v_lshl_add_u32 v209, v209, 2, v207
	global_load_dword v196, v209, s[14:15]
	v_add_u32_e32 v209, 11, v188
	v_med3_i32 v209, v209, -15, 15
	v_lshl_add_u32 v209, v209, 2, v207
	global_load_dword v197, v209, s[14:15]
	v_add_u32_e32 v209, 16, v188
	v_med3_i32 v209, v209, -15, 15
	v_lshl_add_u32 v209, v209, 2, v207
	global_load_dword v198, v209, s[14:15]
	v_add_u32_e32 v209, 17, v188
	v_med3_i32 v209, v209, -15, 15
	v_lshl_add_u32 v209, v209, 2, v207
	global_load_dword v199, v209, s[14:15]
	v_add_u32_e32 v209, 18, v188
	v_med3_i32 v209, v209, -15, 15
	v_lshl_add_u32 v209, v209, 2, v207
	global_load_dword v200, v209, s[14:15]
	v_add_u32_e32 v209, 19, v188
	v_med3_i32 v209, v209, -15, 15
	v_lshl_add_u32 v209, v209, 2, v207
	global_load_dword v201, v209, s[14:15]
	v_add_u32_e32 v209, 24, v188
	v_med3_i32 v209, v209, -15, 15
	v_lshl_add_u32 v209, v209, 2, v207
	global_load_dword v202, v209, s[14:15]
	v_add_u32_e32 v209, 25, v188
	v_med3_i32 v209, v209, -15, 15
	v_lshl_add_u32 v209, v209, 2, v207
	global_load_dword v203, v209, s[14:15]
	v_add_u32_e32 v209, 26, v188
	v_med3_i32 v209, v209, -15, 15
	v_lshl_add_u32 v209, v209, 2, v207
	global_load_dword v204, v209, s[14:15]
	v_add_u32_e32 v209, 27, v188
	v_med3_i32 v209, v209, -15, 15
	v_lshl_add_u32 v209, v209, 2, v207
	global_load_dword v205, v209, s[14:15]
	v_add_u32_e32 v208, 0, v189
	v_cmp_gt_u32_e32 vcc, 16, v208
	s_waitcnt vmcnt(0)
	v_fmamk_f32 v32, v190, 0x3fb8aa3b, v32
	v_add_u32_e32 v211, 1, v189
	v_cmp_gt_u32_e64 s[46:47], 16, v211
	v_cndmask_b32_e32 v32, v210, v32, vcc
	v_fmamk_f32 v33, v191, 0x3fb8aa3b, v33
	v_add_u32_e32 v208, 2, v189
	v_cmp_gt_u32_e32 vcc, 16, v208
	v_cndmask_b32_e64 v33, v210, v33, s[46:47]
	v_fmamk_f32 v34, v192, 0x3fb8aa3b, v34
	v_add_u32_e32 v211, 3, v189
	v_cmp_gt_u32_e64 s[46:47], 16, v211
	v_cndmask_b32_e32 v34, v210, v34, vcc
	v_fmamk_f32 v35, v193, 0x3fb8aa3b, v35
	v_add_u32_e32 v208, 8, v189
	v_cmp_gt_u32_e32 vcc, 16, v208
	v_cndmask_b32_e64 v35, v210, v35, s[46:47]
	v_fmamk_f32 v36, v194, 0x3fb8aa3b, v36
	v_add_u32_e32 v211, 9, v189
	v_cmp_gt_u32_e64 s[46:47], 16, v211
	v_cndmask_b32_e32 v36, v210, v36, vcc
	v_fmamk_f32 v37, v195, 0x3fb8aa3b, v37
	v_add_u32_e32 v208, 10, v189
	v_cmp_gt_u32_e32 vcc, 16, v208
	v_cndmask_b32_e64 v37, v210, v37, s[46:47]
	v_fmamk_f32 v38, v196, 0x3fb8aa3b, v38
	v_add_u32_e32 v211, 11, v189
	v_cmp_gt_u32_e64 s[46:47], 16, v211
	v_cndmask_b32_e32 v38, v210, v38, vcc
	v_fmamk_f32 v39, v197, 0x3fb8aa3b, v39
	v_add_u32_e32 v208, 16, v189
	v_cmp_gt_u32_e32 vcc, 16, v208
	v_cndmask_b32_e64 v39, v210, v39, s[46:47]
	v_fmamk_f32 v40, v198, 0x3fb8aa3b, v40
	v_add_u32_e32 v211, 17, v189
	v_cmp_gt_u32_e64 s[46:47], 16, v211
	v_cndmask_b32_e32 v40, v210, v40, vcc
	v_fmamk_f32 v41, v199, 0x3fb8aa3b, v41
	v_add_u32_e32 v208, 18, v189
	v_cmp_gt_u32_e32 vcc, 16, v208
	v_cndmask_b32_e64 v41, v210, v41, s[46:47]
	v_fmamk_f32 v42, v200, 0x3fb8aa3b, v42
	v_add_u32_e32 v211, 19, v189
	v_cmp_gt_u32_e64 s[46:47], 16, v211
	v_cndmask_b32_e32 v42, v210, v42, vcc
	v_fmamk_f32 v43, v201, 0x3fb8aa3b, v43
	v_add_u32_e32 v208, 24, v189
	v_cmp_gt_u32_e32 vcc, 16, v208
	v_cndmask_b32_e64 v43, v210, v43, s[46:47]
	v_fmamk_f32 v44, v202, 0x3fb8aa3b, v44
	v_add_u32_e32 v211, 25, v189
	v_cmp_gt_u32_e64 s[46:47], 16, v211
	v_cndmask_b32_e32 v44, v210, v44, vcc
	v_fmamk_f32 v45, v203, 0x3fb8aa3b, v45
	v_add_u32_e32 v208, 26, v189
	v_cmp_gt_u32_e32 vcc, 16, v208
	v_cndmask_b32_e64 v45, v210, v45, s[46:47]
	v_fmamk_f32 v46, v204, 0x3fb8aa3b, v46
	v_add_u32_e32 v211, 27, v189
	v_cmp_gt_u32_e64 s[46:47], 16, v211
	v_cndmask_b32_e32 v46, v210, v46, vcc
	v_fmamk_f32 v47, v205, 0x3fb8aa3b, v47
	s_nop 0
	v_cndmask_b32_e64 v47, v210, v47, s[46:47]
	s_branch .LBB0_392
